# plus phase-8 GroupNorm/bonus/gate arithmetic hand-written (12 interleaved wave reductions, rsq instead of IEEE sqrt+div)
# speedup vs baseline: 1.0200x; 1.0015x over previous
.Lgn_loop:
	s_waitcnt vmcnt(0)
	s_mov_b64 s[92:93], s[90:91]
	v_mov_b32_e32 v71, v9
	v_mov_b32_e32 v72, v10
	v_mov_b32_e32 v73, v11
	v_mov_b32_e32 v74, v12
	v_mov_b32_e32 v75, v13
	v_mov_b32_e32 v76, v14
	v_mov_b32_e32 v77, v15
	v_mov_b32_e32 v78, v16
	v_mov_b32_e32 v79, v17
	v_mov_b32_e32 v92, v30
	v_mov_b32_e32 v93, v31
	v_mov_b32_e32 v94, v32
	v_mov_b32_e32 v95, v33
	v_mov_b32_e32 v96, v34
	v_mov_b32_e32 v97, v35
	v_mov_b32_e32 v98, v36
	v_mov_b32_e32 v99, v37
	v_mov_b32_e32 v100, v38
	v_mov_b32_e32 v104, v42
	v_mov_b32_e32 v106, v44
	v_mov_b32_e32 v107, v45
	v_mov_b32_e32 v110, v48
	v_mov_b32_e32 v111, v49
	v_mov_b32_e32 v112, v50
	v_mov_b32_e32 v114, v52
	v_mov_b32_e32 v116, v54
	v_mov_b32_e32 v122, v60
	v_mov_b32_e32 v123, v61
	v_mov_b32_e32 v125, v63
	v_mov_b32_e32 v126, v64
	v_mov_b32_e32 v127, v65
	v_mov_b32_e32 v128, v66
	v_mov_b32_e32 v129, v67
	v_mov_b32_e32 v130, v68
	v_mov_b32_e32 v131, v69
	v_add_u32_e32 v12, 1, v8
	v_mad_i64_i32 v[34:35], s[6:7], v12, s77, v[4:5]
	v_add_u32_e32 v14, 2, v8
	v_add_co_u32_e64 v46, s[8:9], s3, v34
	v_mad_i64_i32 v[36:37], s[6:7], v14, s77, v[4:5]
	s_nop 0
	v_addc_co_u32_e64 v47, s[8:9], 0, v35, s[8:9]
	v_mad_i64_i32 v[10:11], s[6:7], v8, s77, v[4:5]
	v_add_u32_e32 v16, 3, v8
	v_add_co_u32_e64 v48, s[8:9], s3, v36
	v_add_co_u32_e32 v32, vcc, 0x1000, v10
	v_mad_i64_i32 v[38:39], s[6:7], v16, s77, v[4:5]
	v_addc_co_u32_e64 v49, s[8:9], 0, v37, s[8:9]
	v_ashrrev_i32_e32 v9, 31, v8
	v_and_b32_e32 v62, 0x1ff, v19
	v_addc_co_u32_e32 v33, vcc, 0, v11, vcc
	v_add_co_u32_e64 v50, s[8:9], s3, v38
	v_lshlrev_b64 v[30:31], 12, v[8:9]
	global_load_dword v9, v[10:11], off
	global_load_dword v63, v[32:33], off
	v_cmp_ne_u32_e64 s[6:7], 0, v62
	v_addc_co_u32_e64 v51, s[8:9], 0, v39, s[8:9]
	global_load_dword v64, v[46:47], off offset:-4096
	global_load_dword v65, v[46:47], off
	global_load_dword v66, v[48:49], off offset:-4096
	global_load_dword v67, v[48:49], off
	global_load_dword v68, v[50:51], off offset:-4096
	global_load_dword v69, v[50:51], off
	v_ashrrev_i32_e32 v13, 31, v12
	v_ashrrev_i32_e32 v17, 31, v16
	v_subbrev_co_u32_e64 v41, s[6:7], 0, v8, s[6:7]
	v_add_co_u32_e32 v40, vcc, 0x2000, v10
	v_ashrrev_i32_e32 v15, 31, v14
	v_lshlrev_b64 v[12:13], 12, v[12:13]
	v_lshlrev_b64 v[16:17], 12, v[16:17]
	v_mad_i64_i32 v[52:53], s[8:9], v41, s77, v[4:5]
	v_addc_co_u32_e32 v41, vcc, 0, v11, vcc
	v_lshl_add_u64 v[42:43], v[0:1], 0, v[30:31]
	v_lshl_add_u64 v[44:45], v[6:7], 0, v[30:31]
	v_lshlrev_b64 v[14:15], 12, v[14:15]
	v_lshl_add_u64 v[32:33], v[0:1], 0, v[12:13]
	v_lshl_add_u64 v[54:55], v[6:7], 0, v[12:13]
	v_lshl_add_u64 v[48:49], v[6:7], 0, v[16:17]
	v_add_co_u32_e32 v50, vcc, s3, v52
	v_lshl_add_u64 v[56:57], v[0:1], 0, v[14:15]
	v_lshl_add_u64 v[58:59], v[6:7], 0, v[14:15]
	v_lshl_add_u64 v[46:47], v[0:1], 0, v[16:17]
	v_addc_co_u32_e32 v51, vcc, 0, v53, vcc
	v_lshl_add_u64 v[60:61], v[2:3], 0, v[12:13]
	v_lshl_add_u64 v[12:13], v[2:3], 0, v[14:15]
	v_lshl_add_u64 v[10:11], v[2:3], 0, v[16:17]
	global_load_ushort v14, v[44:45], off
	global_load_ushort v15, v[44:45], off offset:2048
	global_load_ushort v16, v[54:55], off
	global_load_ushort v17, v[54:55], off offset:2048
	s_nop 0
	global_load_ushort v44, v[58:59], off
	global_load_ushort v45, v[58:59], off offset:2048
	global_load_ushort v54, v[48:49], off
	s_nop 0
	global_load_ushort v48, v[48:49], off offset:2048
	s_nop 0
	global_load_dword v49, v[52:53], off
	s_nop 0
	global_load_dword v52, v[50:51], off offset:-4096
	s_nop 0
	global_load_dword v50, v[50:51], off
	s_nop 0
	global_load_dword v42, v[42:43], off
	s_nop 0
	global_load_dword v34, v[34:35], off
	s_nop 0
	global_load_dword v35, v[40:41], off
	s_nop 0
	global_load_dword v32, v[32:33], off
	s_nop 0
	global_load_dword v33, v[36:37], off
	s_nop 0
	global_load_dword v36, v[56:57], off
	global_load_dword v37, v[38:39], off
	s_nop 0
	global_load_dword v38, v[46:47], off
	v_cmp_eq_u32_e32 vcc, 0, v62
	v_add_u32_e32 v19, s75, v19
	v_cmp_lt_i32_e64 s[6:7], s79, v19
	s_or_b64 s[68:69], s[6:7], s[68:69]
	v_lshl_add_u64 v[30:31], v[2:3], 0, v[30:31]
	v_add_u32_e32 v8, s76, v8
	s_nop 1
	s_mov_b64 s[90:91], vcc
	v_cndmask_b32_e64 v111, v111, 0, s[92:93]
	v_cndmask_b32_e64 v114, v114, 0, s[92:93]
	v_cndmask_b32_e64 v112, v112, 0, s[92:93]
	v_sub_f32_e32 v168, v111, v71
	v_fma_f32 v140, v25, v168, v71
	v_sub_f32_e32 v169, v114, v125
	v_fma_f32 v144, v26, v169, v125
	v_sub_f32_e32 v170, v112, v97
	v_fma_f32 v148, v27, v170, v97
	v_lshlrev_b32_e32 v76, 16, v76
	v_lshlrev_b32_e32 v77, 16, v77
	v_add_f32_e32 v171, -1.0, v76
	v_fma_f32 v171, v20, v171, 1.0
	v_mul_f32_e32 v171, v144, v171
	v_mul_f32_e32 v156, v140, v171
	v_mul_f32_e32 v156, v21, v156
	v_mov_b32_e32 v152, v104
	v_sub_f32_e32 v168, v71, v96
	v_fma_f32 v141, v25, v168, v96
	v_sub_f32_e32 v169, v125, v126
	v_fma_f32 v145, v26, v169, v126
	v_sub_f32_e32 v170, v97, v127
	v_fma_f32 v149, v27, v170, v127
	v_lshlrev_b32_e32 v78, 16, v78
	v_lshlrev_b32_e32 v79, 16, v79
	v_add_f32_e32 v171, -1.0, v78
	v_fma_f32 v171, v20, v171, 1.0
	v_mul_f32_e32 v171, v145, v171
	v_mul_f32_e32 v157, v141, v171
	v_mul_f32_e32 v157, v21, v157
	v_mov_b32_e32 v153, v94
	v_sub_f32_e32 v168, v96, v95
	v_fma_f32 v142, v25, v168, v95
	v_sub_f32_e32 v169, v126, v128
	v_fma_f32 v146, v26, v169, v128
	v_sub_f32_e32 v170, v127, v129
	v_fma_f32 v150, v27, v170, v129
	v_lshlrev_b32_e32 v106, 16, v106
	v_lshlrev_b32_e32 v107, 16, v107
	v_add_f32_e32 v171, -1.0, v106
	v_fma_f32 v171, v20, v171, 1.0
	v_mul_f32_e32 v171, v146, v171
	v_mul_f32_e32 v158, v142, v171
	v_mul_f32_e32 v158, v21, v158
	v_mov_b32_e32 v154, v98
	v_sub_f32_e32 v168, v95, v99
	v_fma_f32 v143, v25, v168, v99
	v_sub_f32_e32 v169, v128, v130
	v_fma_f32 v147, v26, v169, v130
	v_sub_f32_e32 v170, v129, v131
	v_fma_f32 v151, v27, v170, v131
	v_lshlrev_b32_e32 v116, 16, v116
	v_lshlrev_b32_e32 v110, 16, v110
	v_add_f32_e32 v171, -1.0, v116
	v_fma_f32 v171, v20, v171, 1.0
	v_mul_f32_e32 v171, v147, v171
	v_mul_f32_e32 v159, v143, v171
	v_mul_f32_e32 v159, v21, v159
	v_mov_b32_e32 v155, v100
	v_add_f32_dpp v152, v152, v152 quad_perm:[1,0,3,2] row_mask:0xf bank_mask:0xf bound_ctrl:1
	v_add_f32_dpp v153, v153, v153 quad_perm:[1,0,3,2] row_mask:0xf bank_mask:0xf bound_ctrl:1
	v_add_f32_dpp v154, v154, v154 quad_perm:[1,0,3,2] row_mask:0xf bank_mask:0xf bound_ctrl:1
	v_add_f32_dpp v155, v155, v155 quad_perm:[1,0,3,2] row_mask:0xf bank_mask:0xf bound_ctrl:1
	v_add_f32_dpp v156, v156, v156 quad_perm:[1,0,3,2] row_mask:0xf bank_mask:0xf bound_ctrl:1
	v_add_f32_dpp v157, v157, v157 quad_perm:[1,0,3,2] row_mask:0xf bank_mask:0xf bound_ctrl:1
	v_add_f32_dpp v158, v158, v158 quad_perm:[1,0,3,2] row_mask:0xf bank_mask:0xf bound_ctrl:1
	v_add_f32_dpp v159, v159, v159 quad_perm:[1,0,3,2] row_mask:0xf bank_mask:0xf bound_ctrl:1
	v_add_f32_dpp v152, v152, v152 quad_perm:[2,3,0,1] row_mask:0xf bank_mask:0xf bound_ctrl:1
	v_add_f32_dpp v153, v153, v153 quad_perm:[2,3,0,1] row_mask:0xf bank_mask:0xf bound_ctrl:1
	v_add_f32_dpp v154, v154, v154 quad_perm:[2,3,0,1] row_mask:0xf bank_mask:0xf bound_ctrl:1
	v_add_f32_dpp v155, v155, v155 quad_perm:[2,3,0,1] row_mask:0xf bank_mask:0xf bound_ctrl:1
	v_add_f32_dpp v156, v156, v156 quad_perm:[2,3,0,1] row_mask:0xf bank_mask:0xf bound_ctrl:1
	v_add_f32_dpp v157, v157, v157 quad_perm:[2,3,0,1] row_mask:0xf bank_mask:0xf bound_ctrl:1
	v_add_f32_dpp v158, v158, v158 quad_perm:[2,3,0,1] row_mask:0xf bank_mask:0xf bound_ctrl:1
	v_add_f32_dpp v159, v159, v159 quad_perm:[2,3,0,1] row_mask:0xf bank_mask:0xf bound_ctrl:1
	v_add_f32_dpp v152, v152, v152 row_half_mirror row_mask:0xf bank_mask:0xf bound_ctrl:1
	v_add_f32_dpp v153, v153, v153 row_half_mirror row_mask:0xf bank_mask:0xf bound_ctrl:1
	v_add_f32_dpp v154, v154, v154 row_half_mirror row_mask:0xf bank_mask:0xf bound_ctrl:1
	v_add_f32_dpp v155, v155, v155 row_half_mirror row_mask:0xf bank_mask:0xf bound_ctrl:1
	v_add_f32_dpp v156, v156, v156 row_half_mirror row_mask:0xf bank_mask:0xf bound_ctrl:1
	v_add_f32_dpp v157, v157, v157 row_half_mirror row_mask:0xf bank_mask:0xf bound_ctrl:1
	v_add_f32_dpp v158, v158, v158 row_half_mirror row_mask:0xf bank_mask:0xf bound_ctrl:1
	v_add_f32_dpp v159, v159, v159 row_half_mirror row_mask:0xf bank_mask:0xf bound_ctrl:1
	v_add_f32_dpp v152, v152, v152 row_mirror row_mask:0xf bank_mask:0xf bound_ctrl:1
	v_add_f32_dpp v153, v153, v153 row_mirror row_mask:0xf bank_mask:0xf bound_ctrl:1
	v_add_f32_dpp v154, v154, v154 row_mirror row_mask:0xf bank_mask:0xf bound_ctrl:1
	v_add_f32_dpp v155, v155, v155 row_mirror row_mask:0xf bank_mask:0xf bound_ctrl:1
	v_add_f32_dpp v156, v156, v156 row_mirror row_mask:0xf bank_mask:0xf bound_ctrl:1
	v_add_f32_dpp v157, v157, v157 row_mirror row_mask:0xf bank_mask:0xf bound_ctrl:1
	v_add_f32_dpp v158, v158, v158 row_mirror row_mask:0xf bank_mask:0xf bound_ctrl:1
	v_add_f32_dpp v159, v159, v159 row_mirror row_mask:0xf bank_mask:0xf bound_ctrl:1
	v_mov_b32_e32 v168, v152
	v_mov_b32_e32 v169, v153
	v_mov_b32_e32 v170, v154
	v_mov_b32_e32 v171, v155
	v_mov_b32_e32 v172, v156
	v_mov_b32_e32 v173, v157
	v_mov_b32_e32 v174, v158
	v_mov_b32_e32 v175, v159
	v_permlane16_swap_b32 v152, v168
	v_permlane16_swap_b32 v153, v169
	v_permlane16_swap_b32 v154, v170
	v_permlane16_swap_b32 v155, v171
	v_permlane16_swap_b32 v156, v172
	v_permlane16_swap_b32 v157, v173
	v_permlane16_swap_b32 v158, v174
	v_permlane16_swap_b32 v159, v175
	v_add_f32_e32 v152, v152, v168
	v_add_f32_e32 v153, v153, v169
	v_add_f32_e32 v154, v154, v170
	v_add_f32_e32 v155, v155, v171
	v_add_f32_e32 v156, v156, v172
	v_add_f32_e32 v157, v157, v173
	v_add_f32_e32 v158, v158, v174
	v_add_f32_e32 v159, v159, v175
	v_mov_b32_e32 v168, v152
	v_mov_b32_e32 v169, v153
	v_mov_b32_e32 v170, v154
	v_mov_b32_e32 v171, v155
	v_mov_b32_e32 v172, v156
	v_mov_b32_e32 v173, v157
	v_mov_b32_e32 v174, v158
	v_mov_b32_e32 v175, v159
	v_permlane32_swap_b32 v152, v168
	v_permlane32_swap_b32 v153, v169
	v_permlane32_swap_b32 v154, v170
	v_permlane32_swap_b32 v155, v171
	v_permlane32_swap_b32 v156, v172
	v_permlane32_swap_b32 v157, v173
	v_permlane32_swap_b32 v158, v174
	v_permlane32_swap_b32 v159, v175
	v_add_f32_e32 v152, v152, v168
	v_add_f32_e32 v153, v153, v169
	v_add_f32_e32 v154, v154, v170
	v_add_f32_e32 v155, v155, v171
	v_add_f32_e32 v156, v156, v172
	v_add_f32_e32 v157, v157, v173
	v_add_f32_e32 v158, v158, v174
	v_add_f32_e32 v159, v159, v175
	v_fmamk_f32 v160, v152, 0xbc800000, v104
	v_fmamk_f32 v161, v153, 0xbc800000, v94
	v_fmamk_f32 v162, v154, 0xbc800000, v98
	v_fmamk_f32 v163, v155, 0xbc800000, v100
	v_mul_f32_e32 v164, v160, v160
	v_mul_f32_e32 v165, v161, v161
	v_mul_f32_e32 v166, v162, v162
	v_mul_f32_e32 v167, v163, v163
	v_add_f32_dpp v164, v164, v164 quad_perm:[1,0,3,2] row_mask:0xf bank_mask:0xf bound_ctrl:1
	v_add_f32_dpp v165, v165, v165 quad_perm:[1,0,3,2] row_mask:0xf bank_mask:0xf bound_ctrl:1
	v_add_f32_dpp v166, v166, v166 quad_perm:[1,0,3,2] row_mask:0xf bank_mask:0xf bound_ctrl:1
	v_add_f32_dpp v167, v167, v167 quad_perm:[1,0,3,2] row_mask:0xf bank_mask:0xf bound_ctrl:1
	v_add_f32_dpp v164, v164, v164 quad_perm:[2,3,0,1] row_mask:0xf bank_mask:0xf bound_ctrl:1
	v_add_f32_dpp v165, v165, v165 quad_perm:[2,3,0,1] row_mask:0xf bank_mask:0xf bound_ctrl:1
	v_add_f32_dpp v166, v166, v166 quad_perm:[2,3,0,1] row_mask:0xf bank_mask:0xf bound_ctrl:1
	v_add_f32_dpp v167, v167, v167 quad_perm:[2,3,0,1] row_mask:0xf bank_mask:0xf bound_ctrl:1
	v_add_f32_dpp v164, v164, v164 row_half_mirror row_mask:0xf bank_mask:0xf bound_ctrl:1
	v_add_f32_dpp v165, v165, v165 row_half_mirror row_mask:0xf bank_mask:0xf bound_ctrl:1
	v_add_f32_dpp v166, v166, v166 row_half_mirror row_mask:0xf bank_mask:0xf bound_ctrl:1
	v_add_f32_dpp v167, v167, v167 row_half_mirror row_mask:0xf bank_mask:0xf bound_ctrl:1
	v_add_f32_dpp v164, v164, v164 row_mirror row_mask:0xf bank_mask:0xf bound_ctrl:1
	v_add_f32_dpp v165, v165, v165 row_mirror row_mask:0xf bank_mask:0xf bound_ctrl:1
	v_add_f32_dpp v166, v166, v166 row_mirror row_mask:0xf bank_mask:0xf bound_ctrl:1
	v_add_f32_dpp v167, v167, v167 row_mirror row_mask:0xf bank_mask:0xf bound_ctrl:1
	v_mov_b32_e32 v168, v164
	v_mov_b32_e32 v169, v165
	v_mov_b32_e32 v170, v166
	v_mov_b32_e32 v171, v167
	v_permlane16_swap_b32 v164, v168
	v_permlane16_swap_b32 v165, v169
	v_permlane16_swap_b32 v166, v170
	v_permlane16_swap_b32 v167, v171
	v_add_f32_e32 v164, v164, v168
	v_add_f32_e32 v165, v165, v169
	v_add_f32_e32 v166, v166, v170
	v_add_f32_e32 v167, v167, v171
	v_mov_b32_e32 v168, v164
	v_mov_b32_e32 v169, v165
	v_mov_b32_e32 v170, v166
	v_mov_b32_e32 v171, v167
	v_permlane32_swap_b32 v164, v168
	v_permlane32_swap_b32 v165, v169
	v_permlane32_swap_b32 v166, v170
	v_permlane32_swap_b32 v167, v171
	v_add_f32_e32 v164, v164, v168
	v_add_f32_e32 v165, v165, v169
	v_add_f32_e32 v166, v166, v170
	v_add_f32_e32 v167, v167, v171
	v_mul_f32_e32 v164, 0x3c800000, v164
	v_mul_f32_e32 v165, 0x3c800000, v165
	v_mul_f32_e32 v166, 0x3c800000, v166
	v_mul_f32_e32 v167, 0x3c800000, v167
	v_add_f32_e32 v164, 0x3a27c5ac, v164
	v_add_f32_e32 v165, 0x3a27c5ac, v165
	v_add_f32_e32 v166, 0x3a27c5ac, v166
	v_add_f32_e32 v167, 0x3a27c5ac, v167
	v_rsq_f32_e32 v164, v164
	v_rsq_f32_e32 v165, v165
	v_rsq_f32_e32 v166, v166
	v_rsq_f32_e32 v167, v167
	v_mul_f32_e32 v160, v160, v164
	v_mul_f32_e32 v161, v161, v165
	v_mul_f32_e32 v162, v162, v166
	v_mul_f32_e32 v163, v163, v167
	v_fma_f32 v160, v160, v22, v23
	v_fma_f32 v161, v161, v22, v23
	v_fma_f32 v162, v162, v22, v23
	v_fma_f32 v163, v163, v22, v23
	v_fma_f32 v160, v156, v148, v160
	v_fma_f32 v161, v157, v149, v161
	v_fma_f32 v162, v158, v150, v162
	v_fma_f32 v163, v159, v151, v163
	v_mul_f32_e32 v160, v160, v77
	v_mul_f32_e32 v161, v161, v79
	v_mul_f32_e32 v162, v162, v107
	v_mul_f32_e32 v163, v163, v110
	v_mul_f32_e32 v160, v24, v160
	v_mul_f32_e32 v161, v24, v161
	v_mul_f32_e32 v162, v24, v162
	v_mul_f32_e32 v163, v24, v163
	v_cvt_pk_bf16_f32 v160, v160, v160
	v_cvt_pk_bf16_f32 v161, v161, v161
	v_cvt_pk_bf16_f32 v162, v162, v162
	v_cvt_pk_bf16_f32 v163, v163, v163
	global_store_short v[92:93], v160, off
	global_store_short v[122:123], v161, off
	global_store_short v[74:75], v162, off
	global_store_short v[72:73], v163, off
	s_add_u32 s88, s88, 1
	s_cmp_lt_u32 s88, 16
	s_cbranch_scc1 .Lgn_loop
	s_waitcnt vmcnt(0)
